# FFN-in unit loop: skip reloading per-row rstd when next tile has the same row panel
# speedup vs baseline: 1.0165x; 1.0165x over previous
.LBB0_129:
	v_cndmask_b32_e64 v0, 0, 1, s[38:39]
	v_cmp_ne_u32_e64 s[36:37], 1, v0
	s_andn2_b64 vcc, exec, s[38:39]
	s_cbranch_vccnz .LBB0_131
	s_cmp_eq_u32 s8, s21
	s_cbranch_scc1 .Lffnin_same_pm
	s_lshl_b32 s7, s8, 8
	v_mbcnt_lo_u32_b32 v0, -1, 0
	v_mbcnt_hi_u32_b32 v0, -1, v0
	s_add_i32 s7, s58, s7
	v_ashrrev_i32_e32 v131, 2, v0
	v_and_or_b32 v130, v0, 15, s7
	v_and_b32_e32 v132, -4, v131
	v_ashrrev_i32_e32 v133, 31, v132
	v_ashrrev_i32_e32 v131, 31, v130
	v_lshl_add_u64 v[132:133], v[132:133], 2, s[68:69]
	v_lshlrev_b64 v[134:135], 6, v[130:131]
	v_lshl_add_u64 v[134:135], v[132:133], 0, v[134:135]
	global_load_dwordx4 v[156:159], v[134:135], off
	v_or_b32_e32 v136, 16, v130
	v_ashrrev_i32_e32 v137, 31, v136
	v_lshlrev_b64 v[136:137], 6, v[136:137]
	v_lshl_add_u64 v[136:137], v[132:133], 0, v[136:137]
	global_load_dwordx4 v[166:169], v[136:137], off
	v_or_b32_e32 v136, 32, v130
	v_ashrrev_i32_e32 v137, 31, v136
	v_lshlrev_b64 v[136:137], 6, v[136:137]
	v_lshl_add_u64 v[136:137], v[132:133], 0, v[136:137]
	global_load_dwordx4 v[170:173], v[136:137], off
	v_or_b32_e32 v130, 48, v130
	v_ashrrev_i32_e32 v131, 31, v130
	v_lshlrev_b64 v[130:131], 6, v[130:131]
	v_lshl_add_u64 v[130:131], v[132:133], 0, v[130:131]
	global_load_dwordx4 v[174:177], v[130:131], off
	s_movk_i32 s3, 0x2000
	v_add_co_u32_e32 v130, vcc, s3, v134
	v_lshlrev_b32_e32 v0, 2, v0
	s_nop 0
	v_addc_co_u32_e32 v131, vcc, 0, v135, vcc
	global_load_dwordx4 v[178:181], v[130:131], off
	global_load_dwordx4 v[182:185], v[130:131], off offset:1024
	global_load_dwordx4 v[134:137], v[130:131], off offset:2048
	s_nop 0
	global_load_dwordx4 v[130:133], v[130:131], off offset:3072
	v_xor_b32_e32 v188, 64, v0
	v_xor_b32_e32 v0, 0x80, v0
	s_waitcnt vmcnt(0)
	v_mov_b32_e32 v186, v157
	v_mov_b32_e32 v187, v158
	v_mov_b32_e32 v157, v159
	v_pk_add_f32 v[156:157], v[186:187], v[156:157]
	v_mov_b32_e32 v158, v175
	v_add_f32_e32 v153, v156, v157
	ds_bpermute_b32 v155, v188, v153
	v_mov_b32_e32 v156, v167
	v_mov_b32_e32 v157, v168
	v_mov_b32_e32 v167, v169
	v_pk_add_f32 v[156:157], v[156:157], v[166:167]
	s_waitcnt lgkmcnt(0)
	v_add_f32_e32 v153, v153, v155
	ds_bpermute_b32 v155, v0, v153
	v_mov_b32_e32 v159, v176
	v_mov_b32_e32 v175, v177
	v_pk_add_f32 v[158:159], v[158:159], v[174:175]
	v_mov_b32_e32 v166, v183
	s_waitcnt lgkmcnt(0)
	v_add_f32_e32 v153, v153, v155
	v_add_f32_e32 v155, v156, v157
	ds_bpermute_b32 v156, v188, v155
	v_mov_b32_e32 v157, v172
	v_mov_b32_e32 v167, v184
	v_mov_b32_e32 v183, v185
	v_pk_add_f32 v[166:167], v[166:167], v[182:183]
	s_waitcnt lgkmcnt(0)
	v_add_f32_e32 v155, v155, v156
	ds_bpermute_b32 v156, v0, v155
	v_fmamk_f32 v153, v153, 0x3a800000, v240
	v_rsq_f32_e32 v153, v153
	s_waitcnt lgkmcnt(0)
	v_add_f32_e32 v155, v155, v156
	v_mov_b32_e32 v156, v171
	v_mov_b32_e32 v171, v173
	v_pk_add_f32 v[156:157], v[156:157], v[170:171]
	v_fmamk_f32 v155, v155, 0x3a800000, v240
	v_add_f32_e32 v156, v156, v157
	ds_bpermute_b32 v157, v188, v156
	v_rsq_f32_e32 v155, v155
	s_waitcnt lgkmcnt(0)
	v_add_f32_e32 v156, v156, v157
	ds_bpermute_b32 v157, v0, v156
	s_waitcnt lgkmcnt(0)
	v_add_f32_e32 v156, v156, v157
	v_add_f32_e32 v157, v158, v159
	ds_bpermute_b32 v158, v188, v157
	v_mov_b32_e32 v159, v180
	v_fmamk_f32 v156, v156, 0x3a800000, v240
	v_rsq_f32_e32 v156, v156
	s_waitcnt lgkmcnt(0)
	v_add_f32_e32 v157, v157, v158
	ds_bpermute_b32 v158, v0, v157
	s_waitcnt lgkmcnt(0)
	v_add_f32_e32 v157, v157, v158
	v_mov_b32_e32 v158, v179
	v_mov_b32_e32 v179, v181
	v_pk_add_f32 v[158:159], v[158:159], v[178:179]
	v_fmamk_f32 v157, v157, 0x3a800000, v240
	v_add_f32_e32 v158, v158, v159
	ds_bpermute_b32 v159, v188, v158
	v_rsq_f32_e32 v157, v157
	s_waitcnt lgkmcnt(0)
	v_add_f32_e32 v158, v158, v159
	ds_bpermute_b32 v159, v0, v158
	s_waitcnt lgkmcnt(0)
	v_add_f32_e32 v158, v158, v159
	v_add_f32_e32 v159, v166, v167
	ds_bpermute_b32 v166, v188, v159
	v_mov_b32_e32 v167, v136
	v_mov_b32_e32 v136, v131
	v_mov_b32_e32 v131, v133
	v_fmamk_f32 v158, v158, 0x3a800000, v240
	s_waitcnt lgkmcnt(0)
	v_add_f32_e32 v159, v159, v166
	ds_bpermute_b32 v166, v0, v159
	v_rsq_f32_e32 v158, v158
	s_waitcnt lgkmcnt(0)
	v_add_f32_e32 v159, v159, v166
	v_mov_b32_e32 v166, v135
	v_mov_b32_e32 v135, v137
	v_mov_b32_e32 v137, v132
	v_pk_add_f32 v[134:135], v[166:167], v[134:135]
	v_pk_add_f32 v[130:131], v[136:137], v[130:131]
	v_add_f32_e32 v134, v134, v135
	v_add_f32_e32 v130, v130, v131
	ds_bpermute_b32 v135, v188, v134
	ds_bpermute_b32 v131, v188, v130
	v_fmamk_f32 v159, v159, 0x3a800000, v240
	v_rsq_f32_e32 v159, v159
	s_waitcnt lgkmcnt(1)
	v_add_f32_e32 v134, v134, v135
	s_waitcnt lgkmcnt(0)
	v_add_f32_e32 v130, v130, v131
	ds_bpermute_b32 v135, v0, v134
	ds_bpermute_b32 v0, v0, v130
	s_waitcnt lgkmcnt(1)
	v_add_f32_e32 v134, v134, v135
	s_waitcnt lgkmcnt(0)
	v_add_f32_e32 v0, v130, v0
	v_fmamk_f32 v134, v134, 0x3a800000, v240
	v_fmamk_f32 v0, v0, 0x3a800000, v240
	v_rsq_f32_e32 v134, v134
	v_rsq_f32_e32 v132, v0
	s_branch .LBB0_131
.Lffnin_same_pm:
	v_mov_b32_e32 v132, v151
	v_mov_b32_e32 v134, v154
	v_mov_b32_e32 v159, v160
	v_mov_b32_e32 v158, v161
	v_mov_b32_e32 v157, v162
	v_mov_b32_e32 v156, v163
	v_mov_b32_e32 v155, v164
	v_mov_b32_e32 v153, v165
